# v103 + differential attention: unit-to-workgroup mapping permuted so the workgroups of one XCD share (batch, head group) K/V tiles in its L2
# speedup vs baseline: 1.0048x; 1.0038x over previous
.LBB0_548:
	s_or_b64 exec, exec, s[4:5]
	s_cmpk_gt_i32 s3, 0xff
	s_waitcnt lgkmcnt(0)
	s_barrier
	s_cbranch_scc1 .LBB0_582
	v_mov_b32_e32 v213, 0
	global_load_dword v227, v213, s[52:53]
	v_mbcnt_lo_u32_b32 v0, -1, 0
	s_mov_b32 s5, 0
	s_movk_i32 s44, 0x3000
	v_mov_b64_e32 v[214:215], s[12:13]
	s_mov_b64 s[6:7], 0x1800
	s_movk_i32 s45, 0x1000
	s_movk_i32 s46, 0x110
	s_movk_i32 s47, 0x2000
	s_movk_i32 s48, 0x90
	s_mov_b32 s49, 0xf149f2ca
	s_mov_b32 s50, 0x41000000
	v_mbcnt_hi_u32_b32 v228, -1, v0
	s_mov_b32 s51, 0x800000
	s_movk_i32 s52, 0x4000
	s_mov_b32 s53, 0x8000
	s_mov_b32 s54, 0xc000
	s_mov_b32 s55, 0x10000
	s_mov_b32 s56, 0x14000
	s_mov_b32 s57, 0x18000
	v_mov_b32_e32 v229, 0xf149f2ca
	s_mov_b32 s58, s3
	s_cmpk_lg_u32 s24, 0x100
	s_cbranch_scc1 .Ldf_noremap
	s_and_b32 s58, s3, 7
	s_lshl_b32 s58, s58, 1
	s_lshr_b32 s96, s3, 7
	s_add_i32 s58, s58, s96
	s_lshl_b32 s58, s58, 4
	s_bfe_u32 s96, s3, 0x40003
	s_or_b32 s58, s58, s96
.Ldf_noremap:
	s_branch .LBB0_551
.LBB0_550:
	s_add_i32 s58, s58, s24
	s_cmpk_gt_i32 s58, 0xff
	s_cbranch_scc1 .LBB0_582
